# L2-warm load of the next phase's weight tile as a plain cached load (was system-scope sc0 sc1: eight sharers each re-fetched the lines from memory)
# speedup vs baseline: 1.0110x; 1.0110x over previous
.LBB0_572:
	s_and_b64 vcc, exec, s[6:7]
	s_cbranch_vccz .LBB0_658
	s_mov_b32 s3, -1
	s_nop 0
	v_mbcnt_lo_u32_b32 v0, s3, 0
	v_mbcnt_hi_u32_b32 v0, s3, v0
	v_add_u32_e32 v0, s33, v0
	s_waitcnt vmcnt(0)
	s_nop 0
	v_cmp_eq_u32_e32 vcc, 0, v0
	s_barrier
	s_cmp_eq_u32 s33, 0
	s_cbranch_scc1 .Lwarm_skip_0
	global_load_dword v13, v[10:11], off

.LBB0_587:
	s_mov_b32 s3, -1
	s_nop 0
	v_mbcnt_lo_u32_b32 v0, s3, 0
	v_mbcnt_hi_u32_b32 v0, s3, v0
	v_add_u32_e32 v0, s33, v0
	s_waitcnt vmcnt(0)
	s_nop 0
	v_cmp_eq_u32_e32 vcc, 0, v0
	s_barrier
	s_cmp_eq_u32 s33, 0
	s_cbranch_scc1 .Lwarm_skip_1
	global_load_dword v13, v[10:11], off
